# batch the 32 serialized weight+gamma load pairs in W_UK/W_UV deferred transposes (P1)
# baseline (speedup 1.0000x reference)
.LBB0_736:
	s_andn2_b64 vcc, exec, s[62:63]
	s_cbranch_vccnz .LBB0_738
	s_add_i32 s6, s64, 0xfffffe60
	s_lshl_b32 s15, s6, 8
	s_lshl_b32 s14, s6, 5
	s_and_b32 s6, s15, 0x100
	s_and_b32 s15, s15, 0x3c00
	v_and_or_b32 v0, s14, 64, v217
	s_add_u32 s34, s8, s15
	v_or_b32_e32 v4, s6, v218
	s_addc_u32 s35, s9, 0
	v_lshlrev_b32_e32 v0, 2, v0
	v_mov_b32_e32 v5, v1
	v_lshl_add_u64 v[6:7], s[34:35], 0, v[0:1]
	v_lshlrev_b64 v[34:35], 14, v[4:5]
	v_lshl_add_u64 v[34:35], v[6:7], 0, v[34:35]
	v_lshlrev_b32_e32 v24, 2, v4
	s_mov_b32 s34, 0x20000
	s_mov_b32 s35, 0
	s_and_b32 s14, s14, 0x7c0
	s_lshl_b32 s6, s6, 1
	global_load_dword v51, v24, s[22:23]
	global_load_dword v52, v24, s[22:23] offset:32
	global_load_dword v53, v24, s[22:23] offset:64
	global_load_dword v54, v24, s[22:23] offset:96
	global_load_dword v55, v24, s[22:23] offset:128
	global_load_dword v56, v24, s[22:23] offset:160
	global_load_dword v57, v24, s[22:23] offset:192
	global_load_dword v58, v24, s[22:23] offset:224
	global_load_dword v59, v24, s[22:23] offset:256
	global_load_dword v60, v24, s[22:23] offset:288
	global_load_dword v61, v24, s[22:23] offset:320
	global_load_dword v62, v24, s[22:23] offset:352
	global_load_dword v63, v24, s[22:23] offset:384
	global_load_dword v64, v24, s[22:23] offset:416
	global_load_dword v65, v24, s[22:23] offset:448
	global_load_dword v66, v24, s[22:23] offset:480
	global_load_dword v67, v24, s[22:23] offset:512
	global_load_dword v68, v24, s[22:23] offset:544
	global_load_dword v69, v24, s[22:23] offset:576
	global_load_dword v70, v24, s[22:23] offset:608
	global_load_dword v71, v24, s[22:23] offset:640
	global_load_dword v72, v24, s[22:23] offset:672
	global_load_dword v73, v24, s[22:23] offset:704
	global_load_dword v74, v24, s[22:23] offset:736
	global_load_dword v75, v24, s[22:23] offset:768
	global_load_dword v76, v24, s[22:23] offset:800
	global_load_dword v77, v24, s[22:23] offset:832
	global_load_dword v78, v24, s[22:23] offset:864
	global_load_dword v79, v24, s[22:23] offset:896
	global_load_dword v80, v24, s[22:23] offset:928
	global_load_dword v81, v24, s[22:23] offset:960
	global_load_dword v82, v24, s[22:23] offset:992
	global_load_dword v3, v[34:35], off offset:512 nt
	v_lshl_add_u64 v[34:35], v[34:35], 0, s[34:35]
	global_load_dword v5, v[34:35], off offset:512 nt
	v_lshl_add_u64 v[34:35], v[34:35], 0, s[34:35]
	global_load_dword v8, v[34:35], off offset:512 nt
	v_lshl_add_u64 v[34:35], v[34:35], 0, s[34:35]
	global_load_dword v9, v[34:35], off offset:512 nt
	v_lshl_add_u64 v[34:35], v[34:35], 0, s[34:35]
	global_load_dword v21, v[34:35], off offset:512 nt
	v_lshl_add_u64 v[34:35], v[34:35], 0, s[34:35]
	global_load_dword v22, v[34:35], off offset:512 nt
	v_lshl_add_u64 v[34:35], v[34:35], 0, s[34:35]
	global_load_dword v23, v[34:35], off offset:512 nt
	v_lshl_add_u64 v[34:35], v[34:35], 0, s[34:35]
	global_load_dword v25, v[34:35], off offset:512 nt
	v_lshl_add_u64 v[34:35], v[34:35], 0, s[34:35]
	global_load_dword v26, v[34:35], off offset:512 nt
	v_lshl_add_u64 v[34:35], v[34:35], 0, s[34:35]
	global_load_dword v27, v[34:35], off offset:512 nt
	v_lshl_add_u64 v[34:35], v[34:35], 0, s[34:35]
	global_load_dword v28, v[34:35], off offset:512 nt
	v_lshl_add_u64 v[34:35], v[34:35], 0, s[34:35]
	global_load_dword v29, v[34:35], off offset:512 nt
	v_lshl_add_u64 v[34:35], v[34:35], 0, s[34:35]
	global_load_dword v30, v[34:35], off offset:512 nt
	v_lshl_add_u64 v[34:35], v[34:35], 0, s[34:35]
	global_load_dword v31, v[34:35], off offset:512 nt
	v_lshl_add_u64 v[34:35], v[34:35], 0, s[34:35]
	global_load_dword v32, v[34:35], off offset:512 nt
	v_lshl_add_u64 v[34:35], v[34:35], 0, s[34:35]
	global_load_dword v33, v[34:35], off offset:512 nt
	v_lshl_add_u64 v[34:35], v[34:35], 0, s[34:35]
	s_waitcnt vmcnt(32)
	global_load_dword v36, v[34:35], off offset:512 nt
	v_lshl_add_u64 v[34:35], v[34:35], 0, s[34:35]
	global_load_dword v37, v[34:35], off offset:512 nt
	v_lshl_add_u64 v[34:35], v[34:35], 0, s[34:35]
	global_load_dword v38, v[34:35], off offset:512 nt
	v_lshl_add_u64 v[34:35], v[34:35], 0, s[34:35]
	global_load_dword v39, v[34:35], off offset:512 nt
	v_lshl_add_u64 v[34:35], v[34:35], 0, s[34:35]
	global_load_dword v40, v[34:35], off offset:512 nt
	v_lshl_add_u64 v[34:35], v[34:35], 0, s[34:35]
	global_load_dword v41, v[34:35], off offset:512 nt
	v_lshl_add_u64 v[34:35], v[34:35], 0, s[34:35]
	global_load_dword v42, v[34:35], off offset:512 nt
	v_lshl_add_u64 v[34:35], v[34:35], 0, s[34:35]
	global_load_dword v43, v[34:35], off offset:512 nt
	v_lshl_add_u64 v[34:35], v[34:35], 0, s[34:35]
	global_load_dword v44, v[34:35], off offset:512 nt
	v_lshl_add_u64 v[34:35], v[34:35], 0, s[34:35]
	global_load_dword v45, v[34:35], off offset:512 nt
	v_lshl_add_u64 v[34:35], v[34:35], 0, s[34:35]
	global_load_dword v46, v[34:35], off offset:512 nt
	v_lshl_add_u64 v[34:35], v[34:35], 0, s[34:35]
	global_load_dword v47, v[34:35], off offset:512 nt
	v_lshl_add_u64 v[34:35], v[34:35], 0, s[34:35]
	global_load_dword v48, v[34:35], off offset:512 nt
	v_lshl_add_u64 v[34:35], v[34:35], 0, s[34:35]
	global_load_dword v49, v[34:35], off offset:512 nt
	v_lshl_add_u64 v[34:35], v[34:35], 0, s[34:35]
	global_load_dword v50, v[34:35], off offset:512 nt
	v_lshl_add_u64 v[34:35], v[34:35], 0, s[34:35]
	global_load_dword v0, v[34:35], off offset:512 nt
	s_waitcnt vmcnt(0)
	v_mul_f32_e32 v3, v3, v51
	v_mul_f32_e32 v5, v5, v52
	v_mul_f32_e32 v8, v8, v53
	v_mul_f32_e32 v9, v9, v54
	v_mul_f32_e32 v21, v21, v55
	v_mul_f32_e32 v22, v22, v56
	v_mul_f32_e32 v23, v23, v57
	v_mul_f32_e32 v25, v25, v58
	v_mul_f32_e32 v26, v26, v59
	v_mul_f32_e32 v27, v27, v60
	v_mul_f32_e32 v28, v28, v61
	v_mul_f32_e32 v29, v29, v62
	v_mul_f32_e32 v30, v30, v63
	v_mul_f32_e32 v31, v31, v64
	v_mul_f32_e32 v32, v32, v65
	v_mul_f32_e32 v33, v33, v66
	v_mul_f32_e32 v36, v36, v67
	v_mul_f32_e32 v37, v37, v68
	v_mul_f32_e32 v38, v38, v69
	v_mul_f32_e32 v39, v39, v70
	v_mul_f32_e32 v40, v40, v71
	v_mul_f32_e32 v41, v41, v72
	v_mul_f32_e32 v42, v42, v73
	v_mul_f32_e32 v43, v43, v74
	v_mul_f32_e32 v44, v44, v75
	v_mul_f32_e32 v45, v45, v76
	v_mul_f32_e32 v46, v46, v77
	v_mul_f32_e32 v47, v47, v78
	v_mul_f32_e32 v48, v48, v79
	v_mul_f32_e32 v49, v49, v80
	v_mul_f32_e32 v50, v50, v81
	v_mul_f32_e32 v0, v0, v82
	ds_write_b32 v131, v3
	ds_write_b32 v131, v5 offset:2080
	ds_write_b32 v131, v8 offset:4160
	ds_write_b32 v131, v9 offset:6240
	ds_write_b32 v131, v21 offset:8320
	ds_write_b32 v131, v22 offset:10400
	ds_write_b32 v131, v23 offset:12480
	ds_write_b32 v131, v25 offset:14560
	ds_write_b32 v131, v26 offset:16640
	ds_write_b32 v131, v27 offset:18720
	ds_write_b32 v131, v28 offset:20800
	ds_write_b32 v131, v29 offset:22880
	ds_write_b32 v131, v30 offset:24960
	ds_write_b32 v131, v31 offset:27040
	ds_write_b32 v131, v32 offset:29120
	ds_write_b32 v131, v33 offset:31200
	ds_write_b32 v131, v36 offset:33280
	ds_write_b32 v131, v37 offset:35360
	ds_write_b32 v131, v38 offset:37440
	ds_write_b32 v131, v39 offset:39520
	ds_write_b32 v131, v40 offset:41600
	ds_write_b32 v131, v41 offset:43680
	ds_write_b32 v131, v42 offset:45760
	ds_write_b32 v131, v43 offset:47840
	ds_write_b32 v131, v44 offset:49920
	ds_write_b32 v131, v45 offset:52000
	ds_write_b32 v131, v46 offset:54080
	ds_write_b32 v131, v47 offset:56160
	ds_write_b32 v131, v48 offset:58240
	ds_write_b32 v131, v49 offset:60320
	ds_write_b32 v131, v50 offset:62400
	ds_write_b32 v131, v0 offset:64480
	v_add_lshl_u32 v0, s14, v133, 10
	v_lshl_add_u64 v[4:5], s[52:53], 0, v[0:1]
	s_waitcnt lgkmcnt(0)
	s_barrier
	v_lshl_add_u64 v[8:9], v[4:5], 0, s[6:7]
	ds_read2_b32 v[4:5], v167 offset1:65
	ds_read2_b32 v[6:7], v11 offset0:4 offset1:69
	ds_read2_b32 v[22:23], v167 offset0:130 offset1:195
	ds_read2_b32 v[24:25], v11 offset0:134 offset1:199
	v_mov_b32_e32 v3, v1
	s_waitcnt lgkmcnt(3)
	v_cvt_pk_bf16_f32 v4, v4, v5
	s_waitcnt lgkmcnt(2)
	v_cvt_pk_bf16_f32 v6, v6, v7
	s_waitcnt lgkmcnt(1)
	v_cvt_pk_bf16_f32 v5, v22, v23
	s_waitcnt lgkmcnt(0)
	v_cvt_pk_bf16_f32 v7, v24, v25
	v_lshl_add_u64 v[8:9], v[8:9], 0, v[2:3]
	global_store_dwordx4 v[8:9], v[4:7], off
	ds_read_b32 v0, v168
	ds_read_b32 v3, v168 offset:1040
	ds_read2_b32 v[4:5], v12 offset0:129 offset1:194
	ds_read2_b32 v[6:7], v13 offset0:3 offset1:133
	ds_read2_b32 v[22:23], v14 offset0:70 offset1:135
	s_waitcnt lgkmcnt(2)
	v_cvt_pk_bf16_f32 v4, v0, v4
	s_waitcnt lgkmcnt(1)
	v_cvt_pk_bf16_f32 v5, v5, v6
	v_cvt_pk_bf16_f32 v6, v3, v7
	s_waitcnt lgkmcnt(0)
	v_cvt_pk_bf16_f32 v7, v22, v23
	global_store_dwordx4 v[8:9], v[4:7], off offset:128
	ds_read_b32 v0, v169
	ds_read_b32 v3, v169 offset:1040
	ds_read2_b32 v[4:5], v15 offset0:65 offset1:130
	ds_read2_b32 v[6:7], v16 offset0:67 offset1:197
	ds_read2_b32 v[22:23], v17 offset0:6 offset1:71
	s_waitcnt lgkmcnt(2)
	v_cvt_pk_bf16_f32 v4, v0, v4
	s_waitcnt lgkmcnt(1)
	v_cvt_pk_bf16_f32 v5, v5, v6
	v_cvt_pk_bf16_f32 v6, v3, v7
	s_waitcnt lgkmcnt(0)
	v_cvt_pk_bf16_f32 v7, v22, v23
	global_store_dwordx4 v[8:9], v[4:7], off offset:256
	ds_read_b32 v0, v170
	ds_read_b32 v3, v170 offset:1040
	ds_read2_b32 v[4:5], v18 offset0:1 offset1:66
	ds_read2_b32 v[6:7], v19 offset0:3 offset1:133
	ds_read2_b32 v[22:23], v20 offset0:70 offset1:135
	s_waitcnt lgkmcnt(2)
	v_cvt_pk_bf16_f32 v4, v0, v4
	s_waitcnt lgkmcnt(1)
	v_cvt_pk_bf16_f32 v5, v5, v6
	v_cvt_pk_bf16_f32 v6, v3, v7
	s_waitcnt lgkmcnt(0)
	v_cvt_pk_bf16_f32 v7, v22, v23
	global_store_dwordx4 v[8:9], v[4:7], off offset:384
	s_barrier

.LBB0_739:
	s_andn2_b64 vcc, exec, s[62:63]
	s_cbranch_vccnz .LBB0_741
	s_add_i32 s6, s64, 0xfffffea0
	s_lshl_b32 s15, s6, 8
	s_lshl_b32 s14, s6, 5
	s_and_b32 s6, s15, 0x100
	s_and_b32 s15, s15, 0x3c00
	v_and_or_b32 v0, s14, 64, v217
	s_add_u32 s34, s8, s15
	v_or_b32_e32 v4, s6, v218
	s_addc_u32 s35, s9, 0
	v_lshlrev_b32_e32 v0, 2, v0
	v_mov_b32_e32 v5, v1
	v_lshl_add_u64 v[6:7], s[34:35], 0, v[0:1]
	v_lshlrev_b64 v[34:35], 14, v[4:5]
	v_lshl_add_u64 v[34:35], v[6:7], 0, v[34:35]
	v_lshlrev_b32_e32 v24, 2, v4
	s_mov_b32 s34, 0x20000
	s_mov_b32 s35, 0
	s_and_b32 s14, s14, 0x7c0
	s_lshl_b32 s6, s6, 1
	global_load_dword v51, v24, s[22:23]
	global_load_dword v52, v24, s[22:23] offset:32
	global_load_dword v53, v24, s[22:23] offset:64
	global_load_dword v54, v24, s[22:23] offset:96
	global_load_dword v55, v24, s[22:23] offset:128
	global_load_dword v56, v24, s[22:23] offset:160
	global_load_dword v57, v24, s[22:23] offset:192
	global_load_dword v58, v24, s[22:23] offset:224
	global_load_dword v59, v24, s[22:23] offset:256
	global_load_dword v60, v24, s[22:23] offset:288
	global_load_dword v61, v24, s[22:23] offset:320
	global_load_dword v62, v24, s[22:23] offset:352
	global_load_dword v63, v24, s[22:23] offset:384
	global_load_dword v64, v24, s[22:23] offset:416
	global_load_dword v65, v24, s[22:23] offset:448
	global_load_dword v66, v24, s[22:23] offset:480
	global_load_dword v67, v24, s[22:23] offset:512
	global_load_dword v68, v24, s[22:23] offset:544
	global_load_dword v69, v24, s[22:23] offset:576
	global_load_dword v70, v24, s[22:23] offset:608
	global_load_dword v71, v24, s[22:23] offset:640
	global_load_dword v72, v24, s[22:23] offset:672
	global_load_dword v73, v24, s[22:23] offset:704
	global_load_dword v74, v24, s[22:23] offset:736
	global_load_dword v75, v24, s[22:23] offset:768
	global_load_dword v76, v24, s[22:23] offset:800
	global_load_dword v77, v24, s[22:23] offset:832
	global_load_dword v78, v24, s[22:23] offset:864
	global_load_dword v79, v24, s[22:23] offset:896
	global_load_dword v80, v24, s[22:23] offset:928
	global_load_dword v81, v24, s[22:23] offset:960
	global_load_dword v82, v24, s[22:23] offset:992
	global_load_dword v3, v[34:35], off nt
	v_lshl_add_u64 v[34:35], v[34:35], 0, s[34:35]
	global_load_dword v5, v[34:35], off nt
	v_lshl_add_u64 v[34:35], v[34:35], 0, s[34:35]
	global_load_dword v8, v[34:35], off nt
	v_lshl_add_u64 v[34:35], v[34:35], 0, s[34:35]
	global_load_dword v9, v[34:35], off nt
	v_lshl_add_u64 v[34:35], v[34:35], 0, s[34:35]
	global_load_dword v21, v[34:35], off nt
	v_lshl_add_u64 v[34:35], v[34:35], 0, s[34:35]
	global_load_dword v22, v[34:35], off nt
	v_lshl_add_u64 v[34:35], v[34:35], 0, s[34:35]
	global_load_dword v23, v[34:35], off nt
	v_lshl_add_u64 v[34:35], v[34:35], 0, s[34:35]
	global_load_dword v25, v[34:35], off nt
	v_lshl_add_u64 v[34:35], v[34:35], 0, s[34:35]
	global_load_dword v26, v[34:35], off nt
	v_lshl_add_u64 v[34:35], v[34:35], 0, s[34:35]
	global_load_dword v27, v[34:35], off nt
	v_lshl_add_u64 v[34:35], v[34:35], 0, s[34:35]
	global_load_dword v28, v[34:35], off nt
	v_lshl_add_u64 v[34:35], v[34:35], 0, s[34:35]
	global_load_dword v29, v[34:35], off nt
	v_lshl_add_u64 v[34:35], v[34:35], 0, s[34:35]
	global_load_dword v30, v[34:35], off nt
	v_lshl_add_u64 v[34:35], v[34:35], 0, s[34:35]
	global_load_dword v31, v[34:35], off nt
	v_lshl_add_u64 v[34:35], v[34:35], 0, s[34:35]
	global_load_dword v32, v[34:35], off nt
	v_lshl_add_u64 v[34:35], v[34:35], 0, s[34:35]
	global_load_dword v33, v[34:35], off nt
	v_lshl_add_u64 v[34:35], v[34:35], 0, s[34:35]
	s_waitcnt vmcnt(32)
	global_load_dword v36, v[34:35], off nt
	v_lshl_add_u64 v[34:35], v[34:35], 0, s[34:35]
	global_load_dword v37, v[34:35], off nt
	v_lshl_add_u64 v[34:35], v[34:35], 0, s[34:35]
	global_load_dword v38, v[34:35], off nt
	v_lshl_add_u64 v[34:35], v[34:35], 0, s[34:35]
	global_load_dword v39, v[34:35], off nt
	v_lshl_add_u64 v[34:35], v[34:35], 0, s[34:35]
	global_load_dword v40, v[34:35], off nt
	v_lshl_add_u64 v[34:35], v[34:35], 0, s[34:35]
	global_load_dword v41, v[34:35], off nt
	v_lshl_add_u64 v[34:35], v[34:35], 0, s[34:35]
	global_load_dword v42, v[34:35], off nt
	v_lshl_add_u64 v[34:35], v[34:35], 0, s[34:35]
	global_load_dword v43, v[34:35], off nt
	v_lshl_add_u64 v[34:35], v[34:35], 0, s[34:35]
	global_load_dword v44, v[34:35], off nt
	v_lshl_add_u64 v[34:35], v[34:35], 0, s[34:35]
	global_load_dword v45, v[34:35], off nt
	v_lshl_add_u64 v[34:35], v[34:35], 0, s[34:35]
	global_load_dword v46, v[34:35], off nt
	v_lshl_add_u64 v[34:35], v[34:35], 0, s[34:35]
	global_load_dword v47, v[34:35], off nt
	v_lshl_add_u64 v[34:35], v[34:35], 0, s[34:35]
	global_load_dword v48, v[34:35], off nt
	v_lshl_add_u64 v[34:35], v[34:35], 0, s[34:35]
	global_load_dword v49, v[34:35], off nt
	v_lshl_add_u64 v[34:35], v[34:35], 0, s[34:35]
	global_load_dword v50, v[34:35], off nt
	v_lshl_add_u64 v[34:35], v[34:35], 0, s[34:35]
	global_load_dword v0, v[34:35], off nt
	s_waitcnt vmcnt(0)
	v_mul_f32_e32 v3, v3, v51
	v_mul_f32_e32 v5, v5, v52
	v_mul_f32_e32 v8, v8, v53
	v_mul_f32_e32 v9, v9, v54
	v_mul_f32_e32 v21, v21, v55
	v_mul_f32_e32 v22, v22, v56
	v_mul_f32_e32 v23, v23, v57
	v_mul_f32_e32 v25, v25, v58
	v_mul_f32_e32 v26, v26, v59
	v_mul_f32_e32 v27, v27, v60
	v_mul_f32_e32 v28, v28, v61
	v_mul_f32_e32 v29, v29, v62
	v_mul_f32_e32 v30, v30, v63
	v_mul_f32_e32 v31, v31, v64
	v_mul_f32_e32 v32, v32, v65
	v_mul_f32_e32 v33, v33, v66
	v_mul_f32_e32 v36, v36, v67
	v_mul_f32_e32 v37, v37, v68
	v_mul_f32_e32 v38, v38, v69
	v_mul_f32_e32 v39, v39, v70
	v_mul_f32_e32 v40, v40, v71
	v_mul_f32_e32 v41, v41, v72
	v_mul_f32_e32 v42, v42, v73
	v_mul_f32_e32 v43, v43, v74
	v_mul_f32_e32 v44, v44, v75
	v_mul_f32_e32 v45, v45, v76
	v_mul_f32_e32 v46, v46, v77
	v_mul_f32_e32 v47, v47, v78
	v_mul_f32_e32 v48, v48, v79
	v_mul_f32_e32 v49, v49, v80
	v_mul_f32_e32 v50, v50, v81
	v_mul_f32_e32 v0, v0, v82
	ds_write_b32 v131, v3
	ds_write_b32 v131, v5 offset:2080
	ds_write_b32 v131, v8 offset:4160
	ds_write_b32 v131, v9 offset:6240
	ds_write_b32 v131, v21 offset:8320
	ds_write_b32 v131, v22 offset:10400
	ds_write_b32 v131, v23 offset:12480
	ds_write_b32 v131, v25 offset:14560
	ds_write_b32 v131, v26 offset:16640
	ds_write_b32 v131, v27 offset:18720
	ds_write_b32 v131, v28 offset:20800
	ds_write_b32 v131, v29 offset:22880
	ds_write_b32 v131, v30 offset:24960
	ds_write_b32 v131, v31 offset:27040
	ds_write_b32 v131, v32 offset:29120
	ds_write_b32 v131, v33 offset:31200
	ds_write_b32 v131, v36 offset:33280
	ds_write_b32 v131, v37 offset:35360
	ds_write_b32 v131, v38 offset:37440
	ds_write_b32 v131, v39 offset:39520
	ds_write_b32 v131, v40 offset:41600
	ds_write_b32 v131, v41 offset:43680
	ds_write_b32 v131, v42 offset:45760
	ds_write_b32 v131, v43 offset:47840
	ds_write_b32 v131, v44 offset:49920
	ds_write_b32 v131, v45 offset:52000
	ds_write_b32 v131, v46 offset:54080
	ds_write_b32 v131, v47 offset:56160
	ds_write_b32 v131, v48 offset:58240
	ds_write_b32 v131, v49 offset:60320
	ds_write_b32 v131, v50 offset:62400
	ds_write_b32 v131, v0 offset:64480
	v_add_lshl_u32 v0, s14, v133, 10
	v_lshl_add_u64 v[4:5], s[54:55], 0, v[0:1]
	s_waitcnt lgkmcnt(0)
	s_barrier
	v_lshl_add_u64 v[8:9], v[4:5], 0, s[6:7]
	ds_read2_b32 v[4:5], v167 offset1:65
	ds_read2_b32 v[6:7], v11 offset0:4 offset1:69
	ds_read2_b32 v[22:23], v167 offset0:130 offset1:195
	ds_read2_b32 v[24:25], v11 offset0:134 offset1:199
	v_mov_b32_e32 v3, v1
	s_waitcnt lgkmcnt(3)
	v_cvt_pk_bf16_f32 v4, v4, v5
	s_waitcnt lgkmcnt(2)
	v_cvt_pk_bf16_f32 v6, v6, v7
	s_waitcnt lgkmcnt(1)
	v_cvt_pk_bf16_f32 v5, v22, v23
	s_waitcnt lgkmcnt(0)
	v_cvt_pk_bf16_f32 v7, v24, v25
	v_lshl_add_u64 v[8:9], v[8:9], 0, v[2:3]
	global_store_dwordx4 v[8:9], v[4:7], off
	ds_read_b32 v0, v168
	ds_read_b32 v3, v168 offset:1040
	ds_read2_b32 v[4:5], v12 offset0:129 offset1:194
	ds_read2_b32 v[6:7], v13 offset0:3 offset1:133
	ds_read2_b32 v[22:23], v14 offset0:70 offset1:135
	s_waitcnt lgkmcnt(2)
	v_cvt_pk_bf16_f32 v4, v0, v4
	s_waitcnt lgkmcnt(1)
	v_cvt_pk_bf16_f32 v5, v5, v6
	v_cvt_pk_bf16_f32 v6, v3, v7
	s_waitcnt lgkmcnt(0)
	v_cvt_pk_bf16_f32 v7, v22, v23
	global_store_dwordx4 v[8:9], v[4:7], off offset:128
	ds_read_b32 v0, v169
	ds_read_b32 v3, v169 offset:1040
	ds_read2_b32 v[4:5], v15 offset0:65 offset1:130
	ds_read2_b32 v[6:7], v16 offset0:67 offset1:197
	ds_read2_b32 v[22:23], v17 offset0:6 offset1:71
	s_waitcnt lgkmcnt(2)
	v_cvt_pk_bf16_f32 v4, v0, v4
	s_waitcnt lgkmcnt(1)
	v_cvt_pk_bf16_f32 v5, v5, v6
	v_cvt_pk_bf16_f32 v6, v3, v7
	s_waitcnt lgkmcnt(0)
	v_cvt_pk_bf16_f32 v7, v22, v23
	global_store_dwordx4 v[8:9], v[4:7], off offset:256
	ds_read_b32 v0, v170
	ds_read_b32 v3, v170 offset:1040
	ds_read2_b32 v[4:5], v18 offset0:1 offset1:66
	ds_read2_b32 v[6:7], v19 offset0:3 offset1:133
	ds_read2_b32 v[22:23], v20 offset0:70 offset1:135
	s_waitcnt lgkmcnt(2)
	v_cvt_pk_bf16_f32 v4, v0, v4
	s_waitcnt lgkmcnt(1)
	v_cvt_pk_bf16_f32 v5, v5, v6
	v_cvt_pk_bf16_f32 v6, v3, v7
	s_waitcnt lgkmcnt(0)
	v_cvt_pk_bf16_f32 v7, v22, v23
	global_store_dwordx4 v[8:9], v[4:7], off offset:384
	s_barrier
